# MLA: next-tile row-max hoisted into the MFMA block (4 short max3 chains + v_permlane32_swap instead of LDS bpermute), far tiles skip the serial max tree
# speedup vs baseline: 1.0034x; 1.0031x over previous
; #define LAS __attribute__((address_space(3)))
; DI float fexp2(float x) { return __builtin_amdgcn_exp2f(x); }
; template <int DK, int DV, int MODE> ...
;     ...
;   auto part1 = [&](f32x16 (&st)[2], float mbase, int t) __attribute__((always_inline)) {
;     if (MODE == 0) {
;       const int d0 = rel0 + 64 * t;
;       if (!(d0 - 31 >= 91) && !(d0 + 63 <= -91)) {
;         const int rb_ = d0 - r + 4 * hh + 128;
; #pragma unroll
;         for (int kb = 0; kb < 2; ++kb)
; #pragma unroll
;           for (int i = 0; i < 16; ++i) { int idx = rb_ + 32 * kb + (i & 3) + 8 * (i >> 2); idx = idx < 0 ? 0 : (idx > 256 ? 256 : idx); st[kb][i] += lut[idx]; }
;       }
;     } else {
;       const int ka = ka0 + t;
;       const LAS unsigned char* rp = (const LAS unsigned char*)lut + (ka - ri + 7) * 128;
; #pragma unroll
;       for (int q = 0; q < 8; ++q) { unsigned wv = nacolp[q]; asm volatile("" : "+v"(wv));
; #pragma unroll
;     ...
;   auto part2 = [&](f32x16 (&st)[2], int t) __attribute__((always_inline)) {
;     float ps0 = 0.f, ps1 = 0.f, ps2 = 0.f, ps3 = 0.f;
; #pragma unroll
;     for (int kb = 0; kb < 2; ++kb)
; #pragma unroll
;       for (int i = 0; i < 16; i += 4) {
;         const float p0 = fexp2(st[kb][i]), p1 = fexp2(st[kb][i + 1]), p2 = fexp2(st[kb][i + 2]), p3 = fexp2(st[kb][i + 3]);
;         st[kb][i] = p0; st[kb][i + 1] = p1; st[kb][i + 2] = p2; st[kb][i + 3] = p3; ps0 += p0; ps1 += p1; ps2 += p2; ps3 += p3;
;       }
;     lsum += (ps0 + ps1) + (ps2 + ps3);
;     bf16x8 pf[2][2];
; #pragma unroll
;     for (int kb = 0; kb < 2; ++kb)
; #pragma unroll
;       for (int s = 0; s < 2; ++s) { u32x4 pp; pp.x = cvt_pk(st[kb][8 * s], st[kb][8 * s + 1]); pp.y = cvt_pk(st[kb][8 * s + 2], st[kb][8 * s + 3]); pp.z = cvt_pk(st[kb][8 * s + 4], st[kb][8 * s + 5]); pp.w = cvt_pk(st[kb][8 * s + 6], st[kb][8 * s + 7]); pf[kb][s] = __builtin_bit_cast(bf16x8, pp); }
; #pragma unroll
;     for (int db = 0; db < DV / 32; ++db)
; #pragma unroll
;       for (int kb = 0; kb < 2; ++kb)
; #pragma unroll
;         for (int s = 0; s < 2; ++s) {
;           if (MODE == 1 && ((kb == 1 && s == 1 && cwu == 0) || (kb == 0 && s == 0 && cwu != 0))) continue;
;           const bf16x8 vf = *(const LAS bf16x8*)(lds + ATT_VB + (t & 3) * VBUF + (32 * db + r) * VSTR + (2 * kb + s) * 32 + hh * 16);
;           O[db] = __builtin_amdgcn_mfma_f32_32x32x16_bf16(vf, pf[kb][s], O[db], 0, 0, 0);
;         }
;   };
.LBB0_249:
	s_setprio 1
	s_and_b32 s22, s20, 2
	s_mulk_i32 s22, 0x3400
	s_mulk_i32 s21, 0x2400
	v_add_u32_e32 v252, s22, v160
	ds_read_b128 v[196:199], v252
	ds_read_b128 v[200:203], v252 offset:32
	ds_read_b128 v[216:219], v252 offset:64
	ds_read_b128 v[230:233], v252 offset:96
	ds_read_b128 v[234:237], v252 offset:128
	ds_read_b128 v[244:247], v252 offset:160
	v_add_u32_e32 v243, s21, v163
	v_add_u32_e32 v0, 0x80, v167
	v_cmp_gt_i32_e32 vcc, s78, v0
	v_exp_f32_e32 v82, v82
	v_exp_f32_e32 v83, v83
	v_cndmask_b32_e32 v34, 0, v158, vcc
	v_cmp_lt_i32_e32 vcc, s77, v0
	v_exp_f32_e32 v84, v84
	v_exp_f32_e32 v85, v85
	v_cndmask_b32_e32 v0, v34, v159, vcc
	v_cmp_neq_f32_e32 vcc, s53, v143
	v_exp_f32_e32 v86, v86
	v_exp_f32_e32 v87, v87
	v_cndmask_b32_e32 v142, 0, v143, vcc
	v_sub_f32_e32 v34, v0, v142
	v_mov_b32_e32 v35, v34
	v_mov_b32_e32 v36, v34
	v_mov_b32_e32 v37, v34
	v_mov_b32_e32 v38, v34
	v_mov_b32_e32 v39, v34
	v_mov_b32_e32 v40, v34
	v_mov_b32_e32 v41, v34
	v_mov_b32_e32 v42, v34
	v_mov_b32_e32 v43, v34
	v_mov_b32_e32 v44, v34
	v_mov_b32_e32 v45, v34
	v_mov_b32_e32 v46, v34
	v_mov_b32_e32 v47, v34
	v_mov_b32_e32 v48, v34
	v_mov_b32_e32 v49, v34
	v_exp_f32_e32 v88, v88
	v_exp_f32_e32 v89, v89
	s_waitcnt lgkmcnt(5)
	v_mfma_f32_32x32x16_bf16 v[50:65], v[196:199], v[98:101], v[34:49]
	ds_read_b128 v[196:199], v252 offset:6656
	v_exp_f32_e32 v90, v90
	v_exp_f32_e32 v91, v91
	v_exp_f32_e32 v92, v92
	v_exp_f32_e32 v93, v93
	s_waitcnt lgkmcnt(5)
	v_mfma_f32_32x32x16_bf16 v[50:65], v[200:203], v[102:105], v[50:65]
	ds_read_b128 v[200:203], v252 offset:6688
	v_exp_f32_e32 v94, v94
	v_exp_f32_e32 v95, v95
	v_exp_f32_e32 v96, v96
	v_exp_f32_e32 v97, v97
	s_waitcnt lgkmcnt(5)
	v_mfma_f32_32x32x16_bf16 v[50:65], v[216:219], v[106:109], v[50:65]
	ds_read_b128 v[216:219], v252 offset:6720
	v_exp_f32_e32 v66, v66
	v_exp_f32_e32 v67, v67
	v_cvt_pk_bf16_f32 v168, v82, v83
	v_exp_f32_e32 v68, v68
	s_waitcnt lgkmcnt(5)
	v_mfma_f32_32x32x16_bf16 v[50:65], v[230:233], v[110:113], v[50:65]
	ds_read_b128 v[230:233], v252 offset:6752
	v_exp_f32_e32 v69, v69
	v_cvt_pk_bf16_f32 v169, v84, v85
	v_exp_f32_e32 v70, v70
	v_exp_f32_e32 v71, v71
	s_waitcnt lgkmcnt(5)
	v_mfma_f32_32x32x16_bf16 v[50:65], v[234:237], v[114:117], v[50:65]
	ds_read_b128 v[234:237], v252 offset:6784
	v_cvt_pk_bf16_f32 v170, v86, v87
	v_exp_f32_e32 v72, v72
	v_exp_f32_e32 v73, v73
	v_cvt_pk_bf16_f32 v171, v88, v89
	v_exp_f32_e32 v74, v74
	s_waitcnt lgkmcnt(5)
	v_mfma_f32_32x32x16_bf16 v[50:65], v[244:247], v[118:121], v[50:65]
	ds_read_b128 v[244:247], v252 offset:6816
	v_exp_f32_e32 v75, v75
	v_cvt_pk_bf16_f32 v180, v90, v91
	v_exp_f32_e32 v76, v76
	v_exp_f32_e32 v77, v77
	s_waitcnt lgkmcnt(5)
	v_mfma_f32_32x32x16_bf16 v[34:49], v[196:199], v[98:101], v[34:49]
	ds_read_b128 v[196:199], v243 offset:53248
	v_cvt_pk_bf16_f32 v181, v92, v93
	v_exp_f32_e32 v78, v78
	v_exp_f32_e32 v79, v79
	v_cvt_pk_bf16_f32 v182, v94, v95
	v_exp_f32_e32 v80, v80
	s_waitcnt lgkmcnt(5)
	v_mfma_f32_32x32x16_bf16 v[34:49], v[200:203], v[102:105], v[34:49]
	ds_read_b128 v[200:203], v243 offset:57856
	v_exp_f32_e32 v81, v81
	v_cvt_pk_bf16_f32 v183, v96, v97
	v_add_f32_e32 v172, v82, v86
	v_add_f32_e32 v173, v83, v87
	v_add_f32_e32 v176, v84, v88
	v_add_f32_e32 v179, v85, v89
	s_waitcnt lgkmcnt(5)
	v_mfma_f32_32x32x16_bf16 v[34:49], v[216:219], v[106:109], v[34:49]
	ds_read_b128 v[216:219], v243 offset:53280
	v_add_f32_e32 v172, v90, v172
	v_add_f32_e32 v173, v91, v173
	v_add_f32_e32 v176, v92, v176
	v_add_f32_e32 v179, v93, v179
	v_add_f32_e32 v172, v94, v172
	v_add_f32_e32 v173, v95, v173
	v_add_f32_e32 v176, v96, v176
	s_waitcnt lgkmcnt(5)
	v_mfma_f32_32x32x16_bf16 v[34:49], v[230:233], v[110:113], v[34:49]
	ds_read_b128 v[230:233], v243 offset:57888
	v_add_f32_e32 v179, v97, v179
	v_cvt_pk_bf16_f32 v184, v66, v67
	v_cvt_pk_bf16_f32 v185, v68, v69
	v_cvt_pk_bf16_f32 v186, v70, v71
	v_cvt_pk_bf16_f32 v187, v72, v73
	v_cvt_pk_bf16_f32 v188, v74, v75
	v_cvt_pk_bf16_f32 v189, v76, v77
	s_waitcnt lgkmcnt(5)
	v_mfma_f32_32x32x16_bf16 v[34:49], v[234:237], v[114:117], v[34:49]
	ds_read_b128 v[234:237], v243 offset:53312
	v_cvt_pk_bf16_f32 v190, v78, v79
	v_cvt_pk_bf16_f32 v191, v80, v81
	v_add_f32_e32 v172, v66, v172
	v_add_f32_e32 v173, v67, v173
	v_add_f32_e32 v176, v68, v176
	v_add_f32_e32 v179, v69, v179
	v_add_f32_e32 v172, v70, v172
	s_waitcnt lgkmcnt(5)
	v_mfma_f32_32x32x16_bf16 v[34:49], v[244:247], v[118:121], v[34:49]
	ds_read_b128 v[244:247], v243 offset:57920
	v_add_f32_e32 v173, v71, v173
	v_add_f32_e32 v176, v72, v176
	v_add_f32_e32 v179, v73, v179
	v_add_f32_e32 v172, v74, v172
	v_add_f32_e32 v173, v75, v173
	v_add_f32_e32 v176, v76, v176
	v_add_f32_e32 v179, v77, v179
	s_waitcnt lgkmcnt(5)
	v_mfma_f32_32x32x16_bf16 v[18:33], v[196:199], v[168:171], v[18:33]
	ds_read_b128 v[196:199], v243 offset:53344
	v_add_f32_e32 v172, v78, v172
	v_add_f32_e32 v173, v79, v173
	v_add_f32_e32 v176, v80, v176
	v_add_f32_e32 v179, v81, v179
	v_add_f32_e32 v172, v172, v173
	v_add_f32_e32 v176, v176, v179
	v_max3_f32 v248, v50, v51, v52
	s_waitcnt lgkmcnt(5)
	v_mfma_f32_32x32x16_bf16 v[2:17], v[200:203], v[168:171], v[2:17]
	ds_read_b128 v[200:203], v243 offset:57952
	v_max3_f32 v249, v57, v58, v59
	v_max3_f32 v248, v248, v53, v54
	v_max3_f32 v249, v249, v60, v61
	v_max3_f32 v248, v248, v55, v56
	v_max3_f32 v249, v249, v62, v63
	s_waitcnt lgkmcnt(5)
	v_mfma_f32_32x32x16_bf16 v[18:33], v[216:219], v[180:183], v[18:33]
	v_max3_f32 v250, v34, v35, v36
	v_max3_f32 v251, v41, v42, v43
	v_max3_f32 v250, v250, v37, v38
	v_max3_f32 v251, v251, v44, v45
	v_max3_f32 v250, v250, v39, v40
	v_max3_f32 v251, v251, v46, v47
	v_max3_f32 v248, v248, v249, v64
	s_waitcnt lgkmcnt(4)
	v_mfma_f32_32x32x16_bf16 v[2:17], v[230:233], v[180:183], v[2:17]
	v_max3_f32 v250, v250, v251, v48
	v_max3_f32 v248, v248, v65, v49
	v_max_f32_e32 v248, v248, v250
	v_mov_b32_e32 v249, v248
	s_waitcnt lgkmcnt(3)
	v_mfma_f32_32x32x16_bf16 v[18:33], v[234:237], v[184:187], v[18:33]
	s_waitcnt lgkmcnt(2)
	v_mfma_f32_32x32x16_bf16 v[2:17], v[244:247], v[184:187], v[2:17]
	s_waitcnt lgkmcnt(1)
	v_mfma_f32_32x32x16_bf16 v[18:33], v[196:199], v[188:191], v[18:33]
	s_waitcnt lgkmcnt(0)
	v_mfma_f32_32x32x16_bf16 v[2:17], v[200:203], v[188:191], v[2:17]
	v_add_f32_e32 v0, v172, v176
	v_add_f32_e32 v161, v161, v0
	v_permlane32_swap_b32 v248, v249
	v_max_f32_e32 v174, v248, v249
	s_setprio 0
	s_waitcnt lgkmcnt(0)
	s_barrier

; DI float fexp2(float x) { return __builtin_amdgcn_exp2f(x); }
; template <int DK, int DV, int MODE> ...
;     ...
;     float mx = fmaxf(st[0][0], st[1][0]);
; #pragma unroll
;     for (int i = 1; i < 16; ++i) mx = fmaxf(fmaxf(mx, st[0][i]), st[1][i]);
;     mx = fmaxf(mx, __shfl_xor(mx, 32));
;     const float mabs = mx + mbase;
;     if (__any(mabs > mrun + ATT_THR)) {
;       const float mn = fmaxf(mrun, mabs), alpha = fexp2(mrun - mn); mrun = mn; lsum *= alpha;
; #pragma unroll
;       for (int db = 0; db < DV / 32; ++db)
; #pragma unroll
;         for (int i = 0; i < 16; ++i) O[db][i] *= alpha;
;     }
.Lmla_tree_a:
	v_max_f32_e32 v0, v34, v34
	v_max_f32_e32 v66, v50, v50
	v_max_f32_e32 v0, v66, v0
	v_max3_f32 v0, v0, v51, v35
	v_max3_f32 v0, v0, v52, v36
	v_max3_f32 v0, v0, v53, v37
	v_max3_f32 v0, v0, v54, v38
	v_max3_f32 v0, v0, v55, v39
	v_max3_f32 v0, v0, v56, v40
	v_max3_f32 v0, v0, v57, v41
	v_max3_f32 v0, v0, v58, v42
	v_max3_f32 v0, v0, v59, v43
	v_max3_f32 v0, v0, v60, v44
	v_max3_f32 v0, v0, v61, v45
	v_max3_f32 v0, v0, v62, v46
	v_max3_f32 v0, v0, v63, v47
	v_max3_f32 v0, v0, v64, v48
	v_max3_f32 v0, v0, v65, v49
	ds_bpermute_b32 v66, v162, v0
	s_waitcnt lgkmcnt(0)
	v_max_f32_e32 v66, v66, v66
	v_max_f32_e32 v174, v0, v66
.Lmla_join_a:
	v_pk_add_f32 v[66:67], v[142:143], v[174:175]
	s_nop 0
	v_cmp_gt_f32_e32 vcc, v66, v67
	s_cbranch_vccz .LBB0_271
	v_max_f32_e32 v0, v66, v66
	v_max_f32_e32 v66, v143, v143
	v_max_f32_e32 v66, v66, v0
	v_sub_f32_e32 v0, v143, v66
	v_exp_f32_e32 v0, v0
	v_mov_b32_e32 v143, v66
	v_mul_f32_e32 v161, v161, v0
	v_pk_mul_f32 v[16:17], v[16:17], v[0:1] op_sel_hi:[1,0]
	v_pk_mul_f32 v[14:15], v[14:15], v[0:1] op_sel_hi:[1,0]
	v_pk_mul_f32 v[12:13], v[12:13], v[0:1] op_sel_hi:[1,0]
	v_pk_mul_f32 v[10:11], v[10:11], v[0:1] op_sel_hi:[1,0]
	v_pk_mul_f32 v[8:9], v[8:9], v[0:1] op_sel_hi:[1,0]
	v_pk_mul_f32 v[6:7], v[6:7], v[0:1] op_sel_hi:[1,0]
	v_pk_mul_f32 v[4:5], v[4:5], v[0:1] op_sel_hi:[1,0]
	v_pk_mul_f32 v[2:3], v[2:3], v[0:1] op_sel_hi:[1,0]
	v_pk_mul_f32 v[32:33], v[32:33], v[0:1] op_sel_hi:[1,0]
	v_pk_mul_f32 v[30:31], v[30:31], v[0:1] op_sel_hi:[1,0]
	v_pk_mul_f32 v[28:29], v[28:29], v[0:1] op_sel_hi:[1,0]
	v_pk_mul_f32 v[26:27], v[26:27], v[0:1] op_sel_hi:[1,0]
	v_pk_mul_f32 v[24:25], v[24:25], v[0:1] op_sel_hi:[1,0]
	v_pk_mul_f32 v[22:23], v[22:23], v[0:1] op_sel_hi:[1,0]
	v_pk_mul_f32 v[20:21], v[20:21], v[0:1] op_sel_hi:[1,0]
	v_pk_mul_f32 v[18:19], v[18:19], v[0:1] op_sel_hi:[1,0]

; #define LAS __attribute__((address_space(3)))
; DI float fexp2(float x) { return __builtin_amdgcn_exp2f(x); }
; template <int DK, int DV, int MODE> ...
;     ...
;   auto part1 = [&](f32x16 (&st)[2], float mbase, int t) __attribute__((always_inline)) {
;     if (MODE == 0) {
;       const int d0 = rel0 + 64 * t;
;       if (!(d0 - 31 >= 91) && !(d0 + 63 <= -91)) {
;         const int rb_ = d0 - r + 4 * hh + 128;
; #pragma unroll
;         for (int kb = 0; kb < 2; ++kb)
; #pragma unroll
;           for (int i = 0; i < 16; ++i) { int idx = rb_ + 32 * kb + (i & 3) + 8 * (i >> 2); idx = idx < 0 ? 0 : (idx > 256 ? 256 : idx); st[kb][i] += lut[idx]; }
;       }
;     } else {
;       const int ka = ka0 + t;
;       const LAS unsigned char* rp = (const LAS unsigned char*)lut + (ka - ri + 7) * 128;
; #pragma unroll
;       for (int q = 0; q < 8; ++q) { unsigned wv = nacolp[q]; asm volatile("" : "+v"(wv));
; #pragma unroll
;     ...
;   auto part2 = [&](f32x16 (&st)[2], int t) __attribute__((always_inline)) {
;     float ps0 = 0.f, ps1 = 0.f, ps2 = 0.f, ps3 = 0.f;
; #pragma unroll
;     for (int kb = 0; kb < 2; ++kb)
; #pragma unroll
;       for (int i = 0; i < 16; i += 4) {
;         const float p0 = fexp2(st[kb][i]), p1 = fexp2(st[kb][i + 1]), p2 = fexp2(st[kb][i + 2]), p3 = fexp2(st[kb][i + 3]);
;         st[kb][i] = p0; st[kb][i + 1] = p1; st[kb][i + 2] = p2; st[kb][i + 3] = p3; ps0 += p0; ps1 += p1; ps2 += p2; ps3 += p3;
;       }
;     lsum += (ps0 + ps1) + (ps2 + ps3);
;     bf16x8 pf[2][2];
; #pragma unroll
;     for (int kb = 0; kb < 2; ++kb)
; #pragma unroll
;       for (int s = 0; s < 2; ++s) { u32x4 pp; pp.x = cvt_pk(st[kb][8 * s], st[kb][8 * s + 1]); pp.y = cvt_pk(st[kb][8 * s + 2], st[kb][8 * s + 3]); pp.z = cvt_pk(st[kb][8 * s + 4], st[kb][8 * s + 5]); pp.w = cvt_pk(st[kb][8 * s + 6], st[kb][8 * s + 7]); pf[kb][s] = __builtin_bit_cast(bf16x8, pp); }
; #pragma unroll
;     for (int db = 0; db < DV / 32; ++db)
; #pragma unroll
;       for (int kb = 0; kb < 2; ++kb)
; #pragma unroll
;         for (int s = 0; s < 2; ++s) {
;           if (MODE == 1 && ((kb == 1 && s == 1 && cwu == 0) || (kb == 0 && s == 0 && cwu != 0))) continue;
;           const bf16x8 vf = *(const LAS bf16x8*)(lds + ATT_VB + (t & 3) * VBUF + (32 * db + r) * VSTR + (2 * kb + s) * 32 + hh * 16);
;           O[db] = __builtin_amdgcn_mfma_f32_32x32x16_bf16(vf, pf[kb][s], O[db], 0, 0, 0);
;         }
;   };
.LBB0_273:
	s_setprio 1
	s_add_i32 s25, s19, -4
	s_and_b32 s21, s25, 3
	s_mul_i32 s26, s21, 0x3400
	s_and_b32 s23, s23, 2
	v_add_u32_e32 v252, s26, v160
	s_mul_i32 s26, s23, 0x2400
	ds_read_b128 v[196:199], v252
	ds_read_b128 v[200:203], v252 offset:32
	ds_read_b128 v[216:219], v252 offset:64
	ds_read_b128 v[230:233], v252 offset:96
	ds_read_b128 v[234:237], v252 offset:128
	ds_read_b128 v[244:247], v252 offset:160
	v_add_u32_e32 v243, s26, v163
	v_add_u32_e32 v0, 64, v167
	v_cmp_gt_i32_e32 vcc, s78, v0
	v_exp_f32_e32 v50, v50
	v_exp_f32_e32 v51, v51
	v_cndmask_b32_e32 v66, 0, v158, vcc
	v_cmp_lt_i32_e32 vcc, s77, v0
	v_exp_f32_e32 v52, v52
	v_exp_f32_e32 v53, v53
	v_cndmask_b32_e32 v0, v66, v159, vcc
	v_cmp_neq_f32_e32 vcc, s53, v143
	v_exp_f32_e32 v54, v54
	v_exp_f32_e32 v55, v55
	v_cndmask_b32_e32 v144, 0, v143, vcc
	v_sub_f32_e32 v66, v0, v144
	v_mov_b32_e32 v67, v66
	v_mov_b32_e32 v68, v66
	v_mov_b32_e32 v69, v66
	v_mov_b32_e32 v70, v66
	v_mov_b32_e32 v71, v66
	v_mov_b32_e32 v72, v66
	v_mov_b32_e32 v73, v66
	v_mov_b32_e32 v74, v66
	v_mov_b32_e32 v75, v66
	v_mov_b32_e32 v76, v66
	v_mov_b32_e32 v77, v66
	v_mov_b32_e32 v78, v66
	v_mov_b32_e32 v79, v66
	v_mov_b32_e32 v80, v66
	v_mov_b32_e32 v81, v66
	v_exp_f32_e32 v56, v56
	v_exp_f32_e32 v57, v57
	s_waitcnt lgkmcnt(5)
	v_mfma_f32_32x32x16_bf16 v[82:97], v[196:199], v[98:101], v[66:81]
	ds_read_b128 v[196:199], v252 offset:6656
	v_exp_f32_e32 v58, v58
	v_exp_f32_e32 v59, v59
	v_exp_f32_e32 v60, v60
	v_exp_f32_e32 v61, v61
	s_waitcnt lgkmcnt(5)
	v_mfma_f32_32x32x16_bf16 v[82:97], v[200:203], v[102:105], v[82:97]
	ds_read_b128 v[200:203], v252 offset:6688
	v_exp_f32_e32 v62, v62
	v_exp_f32_e32 v63, v63
	v_exp_f32_e32 v64, v64
	v_exp_f32_e32 v65, v65
	s_waitcnt lgkmcnt(5)
	v_mfma_f32_32x32x16_bf16 v[82:97], v[216:219], v[106:109], v[82:97]
	ds_read_b128 v[216:219], v252 offset:6720
	v_exp_f32_e32 v34, v34
	v_exp_f32_e32 v35, v35
	v_cvt_pk_bf16_f32 v168, v50, v51
	v_exp_f32_e32 v36, v36
	s_waitcnt lgkmcnt(5)
	v_mfma_f32_32x32x16_bf16 v[82:97], v[230:233], v[110:113], v[82:97]
	ds_read_b128 v[230:233], v252 offset:6752
	v_exp_f32_e32 v37, v37
	v_cvt_pk_bf16_f32 v169, v52, v53
	v_exp_f32_e32 v38, v38
	v_exp_f32_e32 v39, v39
	s_waitcnt lgkmcnt(5)
	v_mfma_f32_32x32x16_bf16 v[82:97], v[234:237], v[114:117], v[82:97]
	ds_read_b128 v[234:237], v252 offset:6784
	v_cvt_pk_bf16_f32 v170, v54, v55
	v_exp_f32_e32 v40, v40
	v_exp_f32_e32 v41, v41
	v_cvt_pk_bf16_f32 v171, v56, v57
	v_exp_f32_e32 v42, v42
	s_waitcnt lgkmcnt(5)
	v_mfma_f32_32x32x16_bf16 v[82:97], v[244:247], v[118:121], v[82:97]
	ds_read_b128 v[244:247], v252 offset:6816
	v_exp_f32_e32 v43, v43
	v_cvt_pk_bf16_f32 v180, v58, v59
	v_exp_f32_e32 v44, v44
	v_exp_f32_e32 v45, v45
	s_waitcnt lgkmcnt(5)
	v_mfma_f32_32x32x16_bf16 v[66:81], v[196:199], v[98:101], v[66:81]
	ds_read_b128 v[196:199], v243 offset:53248
	v_cvt_pk_bf16_f32 v181, v60, v61
	v_exp_f32_e32 v46, v46
	v_exp_f32_e32 v47, v47
	v_cvt_pk_bf16_f32 v182, v62, v63
	v_exp_f32_e32 v48, v48
	s_waitcnt lgkmcnt(5)
	v_mfma_f32_32x32x16_bf16 v[66:81], v[200:203], v[102:105], v[66:81]
	ds_read_b128 v[200:203], v243 offset:57856
	v_exp_f32_e32 v49, v49
	v_cvt_pk_bf16_f32 v183, v64, v65
	v_add_f32_e32 v172, v50, v54
	v_add_f32_e32 v173, v51, v55
	v_add_f32_e32 v176, v52, v56
	v_add_f32_e32 v179, v53, v57
	s_waitcnt lgkmcnt(5)
	v_mfma_f32_32x32x16_bf16 v[66:81], v[216:219], v[106:109], v[66:81]
	ds_read_b128 v[216:219], v243 offset:53280
	v_add_f32_e32 v172, v58, v172
	v_add_f32_e32 v173, v59, v173
	v_add_f32_e32 v176, v60, v176
	v_add_f32_e32 v179, v61, v179
	v_add_f32_e32 v172, v62, v172
	v_add_f32_e32 v173, v63, v173
	v_add_f32_e32 v176, v64, v176
	s_waitcnt lgkmcnt(5)
	v_mfma_f32_32x32x16_bf16 v[66:81], v[230:233], v[110:113], v[66:81]
	ds_read_b128 v[230:233], v243 offset:57888
	v_add_f32_e32 v179, v65, v179
	v_cvt_pk_bf16_f32 v184, v34, v35
	v_cvt_pk_bf16_f32 v185, v36, v37
	v_cvt_pk_bf16_f32 v186, v38, v39
	v_cvt_pk_bf16_f32 v187, v40, v41
	v_cvt_pk_bf16_f32 v188, v42, v43
	v_cvt_pk_bf16_f32 v189, v44, v45
	s_waitcnt lgkmcnt(5)
	v_mfma_f32_32x32x16_bf16 v[66:81], v[234:237], v[114:117], v[66:81]
	ds_read_b128 v[234:237], v243 offset:53312
	v_cvt_pk_bf16_f32 v190, v46, v47
	v_cvt_pk_bf16_f32 v191, v48, v49
	v_add_f32_e32 v172, v34, v172
	v_add_f32_e32 v173, v35, v173
	v_add_f32_e32 v176, v36, v176
	v_add_f32_e32 v179, v37, v179
	v_add_f32_e32 v172, v38, v172
	s_waitcnt lgkmcnt(5)
	v_mfma_f32_32x32x16_bf16 v[66:81], v[244:247], v[118:121], v[66:81]
	ds_read_b128 v[244:247], v243 offset:57920
	v_add_f32_e32 v173, v39, v173
	v_add_f32_e32 v176, v40, v176
	v_add_f32_e32 v179, v41, v179
	v_add_f32_e32 v172, v42, v172
	v_add_f32_e32 v173, v43, v173
	v_add_f32_e32 v176, v44, v176
	v_add_f32_e32 v179, v45, v179
	s_waitcnt lgkmcnt(5)
	v_mfma_f32_32x32x16_bf16 v[18:33], v[196:199], v[168:171], v[18:33]
	ds_read_b128 v[196:199], v243 offset:53344
	v_add_f32_e32 v172, v46, v172
	v_add_f32_e32 v173, v47, v173
	v_add_f32_e32 v176, v48, v176
	v_add_f32_e32 v179, v49, v179
	v_add_f32_e32 v172, v172, v173
	v_add_f32_e32 v176, v176, v179
	v_max3_f32 v248, v82, v83, v84
	s_waitcnt lgkmcnt(5)
	v_mfma_f32_32x32x16_bf16 v[2:17], v[200:203], v[168:171], v[2:17]
	ds_read_b128 v[200:203], v243 offset:57952
	v_max3_f32 v249, v89, v90, v91
	v_max3_f32 v248, v248, v85, v86
	v_max3_f32 v249, v249, v92, v93
	v_max3_f32 v248, v248, v87, v88
	v_max3_f32 v249, v249, v94, v95
	s_waitcnt lgkmcnt(5)
	v_mfma_f32_32x32x16_bf16 v[18:33], v[216:219], v[180:183], v[18:33]
	v_max3_f32 v250, v66, v67, v68
	v_max3_f32 v251, v73, v74, v75
	v_max3_f32 v250, v250, v69, v70
	v_max3_f32 v251, v251, v76, v77
	v_max3_f32 v250, v250, v71, v72
	v_max3_f32 v251, v251, v78, v79
	v_max3_f32 v248, v248, v249, v96
	s_waitcnt lgkmcnt(4)
	v_mfma_f32_32x32x16_bf16 v[2:17], v[230:233], v[180:183], v[2:17]
	v_max3_f32 v250, v250, v251, v80
	v_max3_f32 v248, v248, v97, v81
	v_max_f32_e32 v248, v248, v250
	v_mov_b32_e32 v249, v248
	s_waitcnt lgkmcnt(3)
	v_mfma_f32_32x32x16_bf16 v[18:33], v[234:237], v[184:187], v[18:33]
	s_waitcnt lgkmcnt(2)
	v_mfma_f32_32x32x16_bf16 v[2:17], v[244:247], v[184:187], v[2:17]
	s_waitcnt lgkmcnt(1)
	v_mfma_f32_32x32x16_bf16 v[18:33], v[196:199], v[188:191], v[18:33]
	s_waitcnt lgkmcnt(0)
	v_mfma_f32_32x32x16_bf16 v[2:17], v[200:203], v[188:191], v[2:17]
	v_add_f32_e32 v0, v172, v176
	v_add_f32_e32 v161, v161, v0
	v_permlane32_swap_b32 v248, v249
	v_max_f32_e32 v174, v248, v249
	s_setprio 0
	s_cmp_ge_u32 s25, s17
	s_cbranch_scc1 .LBB0_284
	v_cndmask_b32_e64 v0, 0, 1, s[66:67]
	v_cmp_ne_u32_e64 s[50:51], 1, v0
	s_andn2_b64 vcc, exec, s[66:67]
	s_cbranch_vccz .LBB0_285
	s_and_b64 vcc, exec, s[48:49]
	s_cbranch_vccz .LBB0_290

; DI float fexp2(float x) { return __builtin_amdgcn_exp2f(x); }
; template <int DK, int DV, int MODE> ...
;     ...
;     const float mabs = mx + mbase;
;     if (__any(mabs > mrun + ATT_THR)) {
;       const float mn = fmaxf(mrun, mabs), alpha = fexp2(mrun - mn); mrun = mn; lsum *= alpha;
; #pragma unroll
;       for (int db = 0; db < DV / 32; ++db)
; #pragma unroll
;         for (int i = 0; i < 16; ++i) O[db][i] *= alpha;
;     }
.Lmla_join_b:
	v_pk_add_f32 v[34:35], v[144:145], v[174:175]
	s_nop 0
	v_cmp_gt_f32_e32 vcc, v34, v35
	s_cbranch_vccz .LBB0_282
	v_max_f32_e32 v0, v34, v34
	v_max_f32_e32 v34, v143, v143
	v_max_f32_e32 v34, v34, v0
	v_sub_f32_e32 v0, v143, v34
	v_exp_f32_e32 v0, v0
	v_mov_b32_e32 v143, v34
	v_mul_f32_e32 v161, v161, v0
	v_pk_mul_f32 v[16:17], v[16:17], v[0:1] op_sel_hi:[1,0]
	v_pk_mul_f32 v[14:15], v[14:15], v[0:1] op_sel_hi:[1,0]
	v_pk_mul_f32 v[12:13], v[12:13], v[0:1] op_sel_hi:[1,0]
	v_pk_mul_f32 v[10:11], v[10:11], v[0:1] op_sel_hi:[1,0]
	v_pk_mul_f32 v[8:9], v[8:9], v[0:1] op_sel_hi:[1,0]
	v_pk_mul_f32 v[6:7], v[6:7], v[0:1] op_sel_hi:[1,0]
	v_pk_mul_f32 v[4:5], v[4:5], v[0:1] op_sel_hi:[1,0]
	v_pk_mul_f32 v[2:3], v[2:3], v[0:1] op_sel_hi:[1,0]
	v_pk_mul_f32 v[32:33], v[32:33], v[0:1] op_sel_hi:[1,0]
	v_pk_mul_f32 v[30:31], v[30:31], v[0:1] op_sel_hi:[1,0]
	v_pk_mul_f32 v[28:29], v[28:29], v[0:1] op_sel_hi:[1,0]
	v_pk_mul_f32 v[26:27], v[26:27], v[0:1] op_sel_hi:[1,0]
	v_pk_mul_f32 v[24:25], v[24:25], v[0:1] op_sel_hi:[1,0]
	v_pk_mul_f32 v[22:23], v[22:23], v[0:1] op_sel_hi:[1,0]
	v_pk_mul_f32 v[20:21], v[20:21], v[0:1] op_sel_hi:[1,0]
	v_pk_mul_f32 v[18:19], v[18:19], v[0:1] op_sel_hi:[1,0]

; template <int DK, int DV, int MODE> ...
;     ...
;   auto part1 = [&](f32x16 (&st)[2], float mbase, int t) __attribute__((always_inline)) {
;     if (MODE == 0) {
;       const int d0 = rel0 + 64 * t;
;       if (!(d0 - 31 >= 91) && !(d0 + 63 <= -91)) {
;         const int rb_ = d0 - r + 4 * hh + 128;
; #pragma unroll
;         for (int kb = 0; kb < 2; ++kb)
; #pragma unroll
;           for (int i = 0; i < 16; ++i) { int idx = rb_ + 32 * kb + (i & 3) + 8 * (i >> 2); idx = idx < 0 ? 0 : (idx > 256 ? 256 : idx); st[kb][i] += lut[idx]; }
;       }
.Lmla_far_a:
	s_or_b64 exec, exec, s[50:51]
	s_cmp_eq_u32 s18, 0
	s_cbranch_scc1 .Lmla_tree_a
	s_branch .Lmla_join_a
.Lmla_far_b:
	s_or_b64 exec, exec, s[48:49]
	v_mov_b32_e32 v145, v143
	s_branch .Lmla_join_b
